# scan: per-chunk sum-of-squares cross-lane reduction via v_permlane16/32_swap instead of two ds_bpermute round trips
# speedup vs baseline: 1.0157x; 1.0157x over previous
; #define LAS __attribute__((address_space(3)))
; template <bool DRY>
; __device__ __forceinline__ void ssd_chunk(SsdRegs& R, f32x4 (&st)[2], LAS unsigned char* L, bf16_t* BIG, const float* DT, float* SSQY, const SsdItem& I, int c, int tid, int lane, int wave, int li, int pi, int c16, int q4) {
;     ...
;             *(LAS u32x2*)(L + GG + l * PT + (16 * si + 4 * q4) * 2) = w;
;         }
;     }
;     f32x4 stn[2];
;     bf16x8 xfr[2][2], bwf[2];
; #pragma unroll
;     for (int kk = 0; kk < 2; ++kk) { bwf[kk] = SSD_TR(BW, PB, trB, wave, kk); xfr[0][kk] = SSD_TR(XI, PX, trX, 0, kk); xfr[1][kk] = SSD_TR(XI, PX, trX, 1, kk); }
; #pragma unroll
;     for (int pt = 0; pt < 2; ++pt) {
;         f32x4 d = st[pt] * etot;
; #pragma unroll
;         for (int kk = 0; kk < 2; ++kk) d = __builtin_amdgcn_mfma_f32_16x16x32_bf16(bwf[kk], xfr[pt][kk], d, 0, 0, 0);
;         stn[pt] = d;
;     }
;     const bf16x8 xy0 = pi ? xfr[1][0] : xfr[0][0], xy1 = pi ? xfr[1][1] : xfr[0][1];
;     st[0] = stn[0]; st[1] = stn[1];
;     __syncthreads();
;     {
;         f32x4 d1 = (f32x4){0.f, 0.f, 0.f, 0.f}, d2 = (f32x4){0.f, 0.f, 0.f, 0.f};
; #pragma unroll
;         for (int kk = 0; kk < 2; ++kk) d1 = __builtin_amdgcn_mfma_f32_16x16x32_bf16(kk ? xy1 : xy0, SSD_FRAG(GG, PT, 16 * li, kk), d1, 0, 0, 0);
; #pragma unroll
;         for (int kk = 0; kk < 4; ++kk) d2 = __builtin_amdgcn_mfma_f32_16x16x32_bf16(SSD_FRAG(SB, PC, 16 * pi, kk), cfr[kk], d2, 0, 0, 0);
;         const int l = 16 * li + c16; const float ea_l = __expf(*(const LAS float*)(SCW + l * 4));
;         const float zf[4] = {bf_lo(zc.x), bf_hi(zc.x), bf_lo(zc.y), bf_hi(zc.y)};
;         float yg[4], sq = 0.f;
;         const u32x2 xr = *(const LAS u32x2*)(L + XI + l * PX + (16 * pi + 4 * q4) * 2);
;         const float xs[4] = {bf_lo(xr.x), bf_hi(xr.x), bf_lo(xr.y), bf_hi(xr.y)};
; #pragma unroll
;         for (int e = 0; e < 4; ++e) { const float xv = xs[e];
;             const float y = d1[e] + ea_l * d2[e] + I.Dh * xv; yg[e] = y * silu_f(zf[e]); sq += yg[e] * yg[e]; }
;         u32x2 w; w.x = pk2(yg[0], yg[1]); w.y = pk2(yg[2], yg[3]);
;         if (!DRY) *(u32x2*)((char*)BIG + row0 * (BIGW * 2) + I.offZ) = w;
;         sq += __shfl_xor(sq, 16); sq += __shfl_xor(sq, 32);
;         if (DRY) { if (sq == 12345.678f) SSQY[0] = 1.f; } else if (q4 == 0) SSQY[(size_t)(I.h * 4 + I.ph * 2 + pi) * M_ + row0 + l] = sq;
;     }
.LBB0_733:
	v_add_u32_e32 v145, s69, v113
	s_waitcnt lgkmcnt(1)
	ds_write_b64 v145, v[106:107]
	ds_read_b64_tr_b16 v[146:147], v194 offset:17408
	ds_read_b64_tr_b16 v[148:149], v194 offset:18496
	v_exp_f32_e32 v76, s3
	ds_read_b64_tr_b16 v[152:153], v138 offset:35200
	ds_read_b64_tr_b16 v[150:151], v138 offset:34816
	ds_read_b64_tr_b16 v[154:155], v194 offset:26112
	ds_read_b64_tr_b16 v[156:157], v194 offset:27200
	ds_read_b64_tr_b16 v[158:159], v138 offset:37888
	ds_read_b64_tr_b16 v[160:161], v138 offset:38272
	ds_read_b64_tr_b16 v[162:163], v138 offset:34848
	ds_read_b64_tr_b16 v[164:165], v138 offset:35232
	ds_read_b64_tr_b16 v[166:167], v138 offset:37920
	ds_read_b64_tr_b16 v[168:169], v138 offset:38304
	v_pk_mul_f32 v[52:53], v[52:53], v[76:77] op_sel_hi:[1,0]
	v_pk_mul_f32 v[50:51], v[50:51], v[76:77] op_sel_hi:[1,0]
	v_pk_mul_f32 v[56:57], v[56:57], v[76:77] op_sel_hi:[1,0]
	v_pk_mul_f32 v[54:55], v[54:55], v[76:77] op_sel_hi:[1,0]
	s_waitcnt lgkmcnt(8)
	v_mfma_f32_16x16x32_bf16 v[50:53], v[146:149], v[150:153], v[50:53]
	ds_read_b64_tr_b16 v[196:197], v83 offset:53248
	ds_read_b64_tr_b16 v[198:199], v83 offset:53632
	ds_read_b64_tr_b16 v[200:201], v83 offset:56320
	ds_read_b64_tr_b16 v[202:203], v83 offset:56704
	v_add_u32_e32 v143, v112, v111
	s_waitcnt lgkmcnt(0)
	s_barrier
	v_mfma_f32_16x16x32_bf16 v[54:57], v[146:149], v[162:165], v[54:57]
	v_mfma_f32_16x16x32_bf16 v[50:53], v[154:157], v[158:161], v[50:53]
	v_mfma_f32_16x16x32_bf16 v[54:57], v[154:157], v[166:169], v[54:57]
	ds_read_b128 v[150:153], v143
	ds_read_b128 v[154:157], v123
	ds_read_b32 v76, v132
	s_waitcnt lgkmcnt(2)
	v_mfma_f32_16x16x32_bf16 v[146:149], v[196:199], v[150:153], 0
	ds_read_b128 v[150:153], v123 offset:64
	s_waitcnt lgkmcnt(2)
	v_mfma_f32_16x16x32_bf16 v[70:73], v[154:157], v[70:73], 0
	ds_read_b128 v[154:157], v123 offset:128
	s_waitcnt lgkmcnt(1)
	v_mfma_f32_16x16x32_bf16 v[66:69], v[150:153], v[66:69], v[70:73]
	s_nop 4
	ds_read_b128 v[70:73], v123 offset:192
	s_waitcnt lgkmcnt(1)
	v_mfma_f32_16x16x32_bf16 v[62:65], v[154:157], v[62:65], v[66:69]
	s_nop 2
	ds_read_b128 v[66:69], v143 offset:64
	s_waitcnt lgkmcnt(1)
	v_mfma_f32_16x16x32_bf16 v[58:61], v[70:73], v[58:61], v[62:65]
	v_lshlrev_b32_e32 v70, 16, v96
	s_nop 1
	v_exp_f32_e32 v72, v76
	v_mul_f32_e32 v62, 0xbfb8aa3b, v70
	v_exp_f32_e32 v71, v62
	s_waitcnt lgkmcnt(0)
	v_mfma_f32_16x16x32_bf16 v[62:65], v[200:203], v[66:69], v[146:149]
	ds_read_b64 v[66:67], v139 offset:53248
	s_nop 6
	v_fma_f32 v62, v58, v72, v62
	v_add_f32_e32 v58, 1.0, v71
	v_rcp_f32_e32 v76, v58
	v_and_b32_e32 v58, 0xffff0000, v96
	v_mul_f32_e32 v68, 0xbfb8aa3b, v58
	v_exp_f32_e32 v73, v68
	s_waitcnt lgkmcnt(0)
	v_lshlrev_b32_e32 v71, 16, v66
	v_pk_mul_f32 v[68:69], v[76:77], v[70:71]
	v_fma_f32 v63, v59, v72, v63
	v_add_f32_e32 v62, v62, v69
	v_add_f32_e32 v69, 1.0, v73
	v_rcp_f32_e32 v76, v69
	v_and_b32_e32 v59, 0xffff0000, v66
	v_mul_f32_e32 v62, v68, v62
	v_fma_f32 v64, v60, v72, v64
	v_pk_mul_f32 v[58:59], v[76:77], v[58:59]
	v_fmac_f32_e32 v65, v61, v72
	v_add_f32_e32 v59, v63, v59
	v_mul_f32_e32 v63, v58, v59
	v_lshlrev_b32_e32 v58, 16, v97
	v_mul_f32_e32 v59, 0xbfb8aa3b, v58
	v_exp_f32_e32 v68, v59
	v_lshlrev_b32_e32 v59, 16, v67
	v_and_b32_e32 v61, 0xffff0000, v67
	v_mul_f32_e32 v66, v63, v63
	v_add_f32_e32 v60, 1.0, v68
	v_rcp_f32_e32 v76, v60
	v_and_b32_e32 v60, 0xffff0000, v97
	v_mul_f32_e32 v68, 0xbfb8aa3b, v60
	v_exp_f32_e32 v68, v68
	v_pk_mul_f32 v[58:59], v[76:77], v[58:59]
	v_fmac_f32_e32 v66, v62, v62
	v_add_f32_e32 v59, v64, v59
	v_mul_f32_e32 v64, v58, v59
	v_add_f32_e32 v58, 1.0, v68
	v_rcp_f32_e32 v76, v58
	v_fmac_f32_e32 v66, v64, v64
	v_pk_mul_f32 v[58:59], v[76:77], v[60:61]
	s_nop 0
	v_add_f32_e32 v59, v65, v59
	v_mul_f32_e32 v58, v58, v59
	v_fmac_f32_e32 v66, v58, v58
	v_mov_b32_e32 v59, v66
	v_cvt_pk_bf16_f32 v60, v62, v63
	v_cvt_pk_bf16_f32 v61, v64, v58
	v_permlane16_swap_b32 v59, v66
	global_store_dwordx2 v[78:79], v[60:61], off
	v_add_f32_e32 v58, v66, v59
	v_mov_b32_e32 v59, v58
	s_mov_b64 s[0:1], 0xc0000
	v_lshl_add_u64 v[78:79], v[78:79], 0, s[0:1]
	s_nop 0
	v_permlane32_swap_b32 v59, v58
	s_and_saveexec_b64 s[0:1], s[18:19]
	s_cbranch_execz .LBB0_735
	v_add_f32_e32 v60, v58, v59
	global_store_dword v[90:91], v60, off

; #define LAS __attribute__((address_space(3)))
; template <bool DRY>
; __device__ __forceinline__ void ssd_chunk(SsdRegs& R, f32x4 (&st)[2], LAS unsigned char* L, bf16_t* BIG, const float* DT, float* SSQY, const SsdItem& I, int c, int tid, int lane, int wave, int li, int pi, int c16, int q4) {
;     ...
;             *(LAS u32x2*)(L + GG + l * PT + (16 * si + 4 * q4) * 2) = w;
;         }
;     }
;     f32x4 stn[2];
;     bf16x8 xfr[2][2], bwf[2];
; #pragma unroll
;     for (int kk = 0; kk < 2; ++kk) { bwf[kk] = SSD_TR(BW, PB, trB, wave, kk); xfr[0][kk] = SSD_TR(XI, PX, trX, 0, kk); xfr[1][kk] = SSD_TR(XI, PX, trX, 1, kk); }
; #pragma unroll
;     for (int pt = 0; pt < 2; ++pt) {
;         f32x4 d = st[pt] * etot;
; #pragma unroll
;         for (int kk = 0; kk < 2; ++kk) d = __builtin_amdgcn_mfma_f32_16x16x32_bf16(bwf[kk], xfr[pt][kk], d, 0, 0, 0);
;         stn[pt] = d;
;     }
;     const bf16x8 xy0 = pi ? xfr[1][0] : xfr[0][0], xy1 = pi ? xfr[1][1] : xfr[0][1];
;     st[0] = stn[0]; st[1] = stn[1];
;     __syncthreads();
;     {
;         f32x4 d1 = (f32x4){0.f, 0.f, 0.f, 0.f}, d2 = (f32x4){0.f, 0.f, 0.f, 0.f};
; #pragma unroll
;         for (int kk = 0; kk < 2; ++kk) d1 = __builtin_amdgcn_mfma_f32_16x16x32_bf16(kk ? xy1 : xy0, SSD_FRAG(GG, PT, 16 * li, kk), d1, 0, 0, 0);
; #pragma unroll
;         for (int kk = 0; kk < 4; ++kk) d2 = __builtin_amdgcn_mfma_f32_16x16x32_bf16(SSD_FRAG(SB, PC, 16 * pi, kk), cfr[kk], d2, 0, 0, 0);
;         const int l = 16 * li + c16; const float ea_l = __expf(*(const LAS float*)(SCW + l * 4));
;         const float zf[4] = {bf_lo(zc.x), bf_hi(zc.x), bf_lo(zc.y), bf_hi(zc.y)};
;         float yg[4], sq = 0.f;
;         const u32x2 xr = *(const LAS u32x2*)(L + XI + l * PX + (16 * pi + 4 * q4) * 2);
;         const float xs[4] = {bf_lo(xr.x), bf_hi(xr.x), bf_lo(xr.y), bf_hi(xr.y)};
; #pragma unroll
;         for (int e = 0; e < 4; ++e) { const float xv = xs[e];
;             const float y = d1[e] + ea_l * d2[e] + I.Dh * xv; yg[e] = y * silu_f(zf[e]); sq += yg[e] * yg[e]; }
;         u32x2 w; w.x = pk2(yg[0], yg[1]); w.y = pk2(yg[2], yg[3]);
;         if (!DRY) *(u32x2*)((char*)BIG + row0 * (BIGW * 2) + I.offZ) = w;
;         sq += __shfl_xor(sq, 16); sq += __shfl_xor(sq, 32);
;         if (DRY) { if (sq == 12345.678f) SSQY[0] = 1.f; } else if (q4 == 0) SSQY[(size_t)(I.h * 4 + I.ph * 2 + pi) * M_ + row0 + l] = sq;
;     }
.LBB0_746:
	s_waitcnt lgkmcnt(1)
	v_exp_f32_e32 v76, s3
	ds_write_b64 v145, v[100:101]
	ds_read_b64_tr_b16 v[100:101], v194 offset:17408
	ds_read_b64_tr_b16 v[102:103], v194 offset:18496
	ds_read_b64_tr_b16 v[150:151], v138 offset:35200
	ds_read_b64_tr_b16 v[148:149], v138 offset:34816
	ds_read_b64_tr_b16 v[152:153], v194 offset:26112
	ds_read_b64_tr_b16 v[154:155], v194 offset:27200
	ds_read_b64_tr_b16 v[156:157], v138 offset:37888
	ds_read_b64_tr_b16 v[158:159], v138 offset:38272
	ds_read_b64_tr_b16 v[162:163], v138 offset:35232
	ds_read_b64_tr_b16 v[160:161], v138 offset:34848
	ds_read_b64_tr_b16 v[166:167], v138 offset:38304
	v_pk_mul_f32 v[52:53], v[52:53], v[76:77] op_sel_hi:[1,0]
	v_pk_mul_f32 v[50:51], v[50:51], v[76:77] op_sel_hi:[1,0]
	ds_read_b64_tr_b16 v[164:165], v138 offset:37920
	v_pk_mul_f32 v[56:57], v[56:57], v[76:77] op_sel_hi:[1,0]
	v_pk_mul_f32 v[54:55], v[54:55], v[76:77] op_sel_hi:[1,0]
	s_waitcnt lgkmcnt(8)
	v_mfma_f32_16x16x32_bf16 v[50:53], v[100:103], v[148:151], v[50:53]
	ds_read_b64_tr_b16 v[196:197], v83 offset:59392
	ds_read_b64_tr_b16 v[198:199], v83 offset:59776
	ds_read_b64_tr_b16 v[200:201], v83 offset:62464
	ds_read_b64_tr_b16 v[202:203], v83 offset:62848
	s_waitcnt lgkmcnt(0)
	s_barrier
	v_mfma_f32_16x16x32_bf16 v[54:57], v[100:103], v[160:163], v[54:57]
	v_mfma_f32_16x16x32_bf16 v[50:53], v[152:155], v[156:159], v[50:53]
	ds_read_b128 v[148:151], v143
	v_mfma_f32_16x16x32_bf16 v[54:57], v[152:155], v[164:167], v[54:57]
	ds_read_b128 v[152:155], v125
	s_waitcnt lgkmcnt(1)
	v_mfma_f32_16x16x32_bf16 v[100:103], v[196:199], v[148:151], 0
	ds_read_b128 v[148:151], v125 offset:64
	s_waitcnt lgkmcnt(1)
	v_mfma_f32_16x16x32_bf16 v[70:73], v[152:155], v[70:73], 0
	ds_read_b128 v[152:155], v125 offset:128
	s_waitcnt lgkmcnt(1)
	v_mfma_f32_16x16x32_bf16 v[66:69], v[148:151], v[66:69], v[70:73]
	s_nop 4
	ds_read_b128 v[70:73], v125 offset:192
	ds_read_b32 v76, v132
	s_waitcnt lgkmcnt(2)
	v_mfma_f32_16x16x32_bf16 v[62:65], v[152:155], v[62:65], v[66:69]
	s_nop 2
	v_lshlrev_b32_e32 v68, 16, v92
	s_waitcnt lgkmcnt(1)
	v_mfma_f32_16x16x32_bf16 v[58:61], v[70:73], v[58:61], v[62:65]
	v_mul_f32_e32 v69, 0xbfb8aa3b, v68
	v_exp_f32_e32 v69, v69
	s_waitcnt lgkmcnt(0)
	v_exp_f32_e32 v70, v76
	ds_read_b128 v[62:65], v143 offset:64
	ds_read_b64 v[66:67], v139 offset:59392
	s_waitcnt lgkmcnt(1)
	v_mfma_f32_16x16x32_bf16 v[62:65], v[200:203], v[62:65], v[100:103]
	s_nop 7
	v_fma_f32 v62, v58, v70, v62
	v_add_f32_e32 v58, 1.0, v69
	v_rcp_f32_e32 v76, v58
	v_and_b32_e32 v58, 0xffff0000, v92
	v_mul_f32_e32 v69, 0xbfb8aa3b, v58
	v_exp_f32_e32 v71, v69
	s_waitcnt lgkmcnt(0)
	v_lshlrev_b32_e32 v69, 16, v66
	v_pk_mul_f32 v[68:69], v[76:77], v[68:69]
	v_fma_f32 v63, v59, v70, v63
	v_add_f32_e32 v62, v62, v69
	v_add_f32_e32 v69, 1.0, v71
	v_rcp_f32_e32 v76, v69
	v_and_b32_e32 v59, 0xffff0000, v66
	v_mul_f32_e32 v62, v68, v62
	v_fma_f32 v64, v60, v70, v64
	v_pk_mul_f32 v[58:59], v[76:77], v[58:59]
	v_fmac_f32_e32 v65, v61, v70
	v_add_f32_e32 v59, v63, v59
	v_mul_f32_e32 v63, v58, v59
	v_lshlrev_b32_e32 v58, 16, v93
	v_mul_f32_e32 v59, 0xbfb8aa3b, v58
	v_exp_f32_e32 v68, v59
	v_lshlrev_b32_e32 v59, 16, v67
	v_and_b32_e32 v61, 0xffff0000, v67
	v_mul_f32_e32 v66, v63, v63
	v_add_f32_e32 v60, 1.0, v68
	v_rcp_f32_e32 v76, v60
	v_and_b32_e32 v60, 0xffff0000, v93
	v_mul_f32_e32 v68, 0xbfb8aa3b, v60
	v_exp_f32_e32 v68, v68
	v_pk_mul_f32 v[58:59], v[76:77], v[58:59]
	v_fmac_f32_e32 v66, v62, v62
	v_add_f32_e32 v59, v64, v59
	v_mul_f32_e32 v64, v58, v59
	v_add_f32_e32 v58, 1.0, v68
	v_rcp_f32_e32 v76, v58
	v_fmac_f32_e32 v66, v64, v64
	v_pk_mul_f32 v[58:59], v[76:77], v[60:61]
	s_nop 0
	v_add_f32_e32 v59, v65, v59
	v_mul_f32_e32 v58, v58, v59
	v_fmac_f32_e32 v66, v58, v58
	v_mov_b32_e32 v59, v66
	v_cvt_pk_bf16_f32 v60, v62, v63
	v_cvt_pk_bf16_f32 v61, v64, v58
	v_permlane16_swap_b32 v59, v66
	global_store_dwordx2 v[78:79], v[60:61], off
	v_add_f32_e32 v58, v66, v59
	v_mov_b32_e32 v59, v58
	s_mov_b64 s[0:1], 0xc0000
	v_lshl_add_u64 v[78:79], v[78:79], 0, s[0:1]
	s_nop 0
	v_permlane32_swap_b32 v59, v58
	s_and_saveexec_b64 s[0:1], s[18:19]
	s_cbranch_execz .LBB0_719
	v_add_f32_e32 v60, v58, v59
	global_store_dword v[90:91], v60, off offset:256
	s_branch .LBB0_719
